# plus E3 phase runs its 64 sample-row half tiles before the wide tiles (less tail: the late wide tiles run on a less contended chip)
# speedup vs baseline: 1.0060x; 1.0060x over previous
;   DI u16* xb() const { return (u16*)(ws + WS_xb); }
;   DI u16* Wt_out_e() const { return (u16*)(ws + WS_Wt_out_e); }
;   DI u16* A2() const { return (u16*)(ws + WS_A2); }
; __global__ void __launch_bounds__(256, 2) fwd_megakernel(Params p) {
;     ...
;   xcd_barrier(xb);
;   for (TileSched ts = tile_sched(128 * 4); ts.t < ts.hi; ts.t += ts.step) {
;     const int mt = ts.t >> 2, n2 = ts.t & 3;
;     gemm_tile_wide<1024>(p.A2(), 1024, p.Wt_out_e(), 1024, mt * 128, n2 * 256, smem, [&](int half) { epi_out(p, mt, 2 * n2 + half, (const float*)smem, 0); });
;   }
;   for (TileSched ts = tile_sched(64); ts.t < ts.hi; ts.t += ts.step) {
;     const int hm = ts.t >> 3, nt = ts.t & 7;
;     gemm_tile<1024, 64>(p.A2(), 1024, p.Wt_out_e(), 1024, TP + hm * 64, nt * 128, smem);
;     epi_out(p, 128 + (hm >> 1), nt, (const float*)smem, 0, (hm & 1) * 64, 8);
;   }
.LBB0_637:
	s_or_b64 exec, exec, s[0:1]
	s_waitcnt lgkmcnt(0)
	s_barrier
	s_branch .LBB0_776
.Lsf_e3_wide:
	v_readlane_b32 s0, v247, 36
	v_readlane_b32 s1, v247, 37
	s_and_b64 vcc, exec, s[0:1]
	v_readlane_b32 s0, v247, 4
	s_movk_i32 s18, 0x200
	s_mov_b32 s5, s0
	v_readlane_b32 s4, v247, 26
	s_waitcnt lgkmcnt(0)
	s_barrier
	v_readlane_b32 s1, v247, 5
	s_cbranch_vccz .LBB0_639
	s_cmp_ge_i32 s5, s18
	s_cbranch_scc0 .LBB0_640
	s_branch .LBB0_813
